# S-phase K-fragment prefetch with 4 buffers and accumulator splat cleanup in stick-breaking prompt tile
# baseline (speedup 1.0000x reference)
; #define LAS __attribute__((address_space(3)))
; DI float fexp2(float x) { return __builtin_amdgcn_exp2f(x); }
; DI float frcp(float x) { return __builtin_amdgcn_rcpf(x); }
; #define MFMA32(a, b, c) __builtin_amdgcn_mfma_f32_32x32x16_bf16((a), (b), (c), 0, 0, 0)
; DI void prompt_tile(const LAS unsigned char* kc, const LAS unsigned char* vc, const bf16x8 (&qf)[4], f32x16 (&accO)[2], float& carry, float bias2, int key0, int Q0, int r, int h2) {
;     ...
;     if (key0 < Q0 + 31) {
;         f32x16 sk[2];
; #pragma unroll
;         for (int kb = 0; kb < 2; ++kb) {
; #pragma unroll
;             for (int i = 0; i < 16; ++i) sk[kb][i] = bias2;
; #pragma unroll
;             for (int s = 0; s < 4; ++s) { const bf16x8 a = *(const LAS bf16x8*)(kc + (32 * kb + r) * (KLD * 2) + (16 * s + 8 * h2) * 2); sk[kb] = MFMA32(a, qf[s], sk[kb]); }
;         }
;         const bool need_mask = key0 + 63 >= Q0;
;         f32x2 kp[2][8];
; #pragma unroll
;         for (int kb = 0; kb < 2; ++kb)
; #pragma unroll
;             for (int pq = 0; pq < 8; ++pq) {
;                 f32x2 e2; e2.x = fexp2(sk[kb][2 * pq]); e2.y = fexp2(sk[kb][2 * pq + 1]);
;                 const f32x2 d2 = e2 + 1.0f;
;                 f32x2 k2; k2.x = frcp(d2.x); k2.y = frcp(d2.y);
;                 kp[kb][pq] = k2;
;             }
.LBB0_569:
	s_max_i32 s12, s75, 2
	s_lshl_b32 s12, s12, 6
	s_addk_i32 s12, 0xff80
	s_ashr_i32 s13, s12, 31
	s_lshl_b64 s[14:15], s[12:13], 10
	v_lshl_add_u64 v[4:5], v[208:209], 0, s[14:15]
	global_load_dwordx4 v[176:179], v[4:5], off
	v_lshl_add_u64 v[4:5], s[12:13], 1, v[210:211]
	global_load_dwordx4 v[180:183], v[4:5], off
	v_cndmask_b32_e64 v3, 0, 1, s[60:61]
	v_readlane_b32 s16, v243, 24
	v_cmp_ne_u32_e64 s[18:19], 1, v3
	s_andn2_b64 vcc, exec, s[60:61]
	v_readlane_b32 s17, v243, 25
	s_cbranch_vccnz .LBB0_576
	s_lshl_b32 s12, s75, 6
	s_add_i32 s13, s74, 31
	s_cmp_ge_i32 s12, s13
	s_cbranch_scc1 .LBB0_574
	s_mul_i32 s13, s2, 0x2400
	v_add3_u32 v3, v218, s13, v219
	ds_read_b128 v[224:227], v3
	ds_read_b128 v[228:231], v3 offset:32
	ds_read_b128 v[248:251], v3 offset:64
	ds_read_b128 v[252:255], v3 offset:96
	v_mov_b32_e32 v39, v38
	v_mov_b64_e32 v[40:41], v[38:39]
	v_mov_b64_e32 v[42:43], v[38:39]
	v_mov_b64_e32 v[44:45], v[38:39]
	v_mov_b64_e32 v[46:47], v[38:39]
	v_mov_b64_e32 v[48:49], v[38:39]
	v_mov_b64_e32 v[50:51], v[38:39]
	v_mov_b64_e32 v[52:53], v[38:39]
	v_mov_b64_e32 v[54:55], v[38:39]
	s_or_b32 s13, s12, 63
	s_cmp_lt_i32 s13, s74
	s_waitcnt lgkmcnt(3)
	v_mfma_f32_32x32x16_bf16 v[56:71], v[224:227], v[72:75], v[40:55]
	ds_read_b128 v[224:227], v3 offset:4608
	s_waitcnt lgkmcnt(3)
	v_mfma_f32_32x32x16_bf16 v[56:71], v[228:231], v[84:87], v[56:71]
	ds_read_b128 v[228:231], v3 offset:4640
	s_waitcnt lgkmcnt(3)
	v_mfma_f32_32x32x16_bf16 v[56:71], v[248:251], v[80:83], v[56:71]
	ds_read_b128 v[248:251], v3 offset:4672
	s_waitcnt lgkmcnt(3)
	v_mfma_f32_32x32x16_bf16 v[56:71], v[252:255], v[76:79], v[56:71]
	ds_read_b128 v[252:255], v3 offset:4704
	s_waitcnt lgkmcnt(3)
	v_mfma_f32_32x32x16_bf16 v[40:55], v[224:227], v[72:75], v[40:55]
	s_nop 8
	v_exp_f32_e32 v4, v56
	v_exp_f32_e32 v5, v57
	s_nop 0
	v_pk_add_f32 v[4:5], v[4:5], 1.0 op_sel_hi:[1,0]
	s_waitcnt lgkmcnt(2)
	v_mfma_f32_32x32x16_bf16 v[40:55], v[228:231], v[84:87], v[40:55]
	v_rcp_f32_e32 v56, v4
	v_rcp_f32_e32 v57, v5
	v_exp_f32_e32 v4, v58
	v_exp_f32_e32 v5, v59
	v_exp_f32_e32 v58, v60
	v_exp_f32_e32 v59, v61
	s_waitcnt lgkmcnt(1)
	v_mfma_f32_32x32x16_bf16 v[40:55], v[248:251], v[80:83], v[40:55]
	v_add_f32_e64 v58, v58, 1.0
	v_add_f32_e64 v59, v59, 1.0
	v_exp_f32_e32 v60, v66
	v_rcp_f32_e32 v216, v58
	v_rcp_f32_e32 v217, v59
	v_exp_f32_e32 v58, v62
	v_exp_f32_e32 v59, v63
	s_waitcnt lgkmcnt(0)
	v_mfma_f32_32x32x16_bf16 v[40:55], v[252:255], v[76:79], v[40:55]
	v_add_f32_e64 v58, v58, 1.0
	v_add_f32_e64 v59, v59, 1.0
	v_exp_f32_e32 v61, v67
	v_rcp_f32_e32 v62, v58
	v_rcp_f32_e32 v63, v59
	v_exp_f32_e32 v58, v64
	v_exp_f32_e32 v59, v65
	v_exp_f32_e32 v64, v68
	s_nop 3
	v_exp_f32_e32 v44, v44
	v_exp_f32_e32 v45, v45
	v_exp_f32_e32 v65, v69
	v_exp_f32_e32 v66, v70
	v_exp_f32_e32 v67, v71
	v_pk_add_f32 v[44:45], v[44:45], 1.0 op_sel_hi:[1,0]
	v_exp_f32_e32 v40, v40
	v_rcp_f32_e32 v68, v44
	v_rcp_f32_e32 v69, v45
	v_exp_f32_e32 v44, v46
	v_exp_f32_e32 v45, v47
	v_exp_f32_e32 v41, v41
	v_exp_f32_e32 v42, v42
	v_exp_f32_e32 v43, v43
	v_pk_add_f32 v[44:45], v[44:45], 1.0 op_sel_hi:[1,0]
	v_exp_f32_e32 v46, v50
	v_rcp_f32_e32 v70, v44
	v_rcp_f32_e32 v71, v45
	v_exp_f32_e32 v44, v48
	v_exp_f32_e32 v45, v49
	v_exp_f32_e32 v47, v51
	v_exp_f32_e32 v48, v52
	v_exp_f32_e32 v49, v53
	v_exp_f32_e32 v50, v54
	v_exp_f32_e32 v51, v55
	v_pk_add_f32 v[4:5], v[4:5], 1.0 op_sel_hi:[1,0]
	v_pk_add_f32 v[58:59], v[58:59], 1.0 op_sel_hi:[1,0]
	v_pk_add_f32 v[60:61], v[60:61], 1.0 op_sel_hi:[1,0]
	v_pk_add_f32 v[64:65], v[64:65], 1.0 op_sel_hi:[1,0]
	v_pk_add_f32 v[66:67], v[66:67], 1.0 op_sel_hi:[1,0]
	v_pk_add_f32 v[40:41], v[40:41], 1.0 op_sel_hi:[1,0]
	v_pk_add_f32 v[42:43], v[42:43], 1.0 op_sel_hi:[1,0]
	v_pk_add_f32 v[44:45], v[44:45], 1.0 op_sel_hi:[1,0]
	v_pk_add_f32 v[46:47], v[46:47], 1.0 op_sel_hi:[1,0]
	v_pk_add_f32 v[48:49], v[48:49], 1.0 op_sel_hi:[1,0]
	v_pk_add_f32 v[50:51], v[50:51], 1.0 op_sel_hi:[1,0]
	v_rcp_f32_e32 v4, v4
	v_rcp_f32_e32 v5, v5
	v_rcp_f32_e32 v58, v58
	v_rcp_f32_e32 v59, v59
	v_rcp_f32_e32 v60, v60
	v_rcp_f32_e32 v61, v61
	v_rcp_f32_e32 v64, v64
	v_rcp_f32_e32 v65, v65
	v_rcp_f32_e32 v66, v66
	v_rcp_f32_e32 v67, v67
	v_rcp_f32_e32 v40, v40
	v_rcp_f32_e32 v41, v41
	v_rcp_f32_e32 v42, v42
	v_rcp_f32_e32 v43, v43
	v_rcp_f32_e32 v44, v44
	v_rcp_f32_e32 v45, v45
	v_rcp_f32_e32 v46, v46
	v_rcp_f32_e32 v47, v47
	v_rcp_f32_e32 v48, v48
	v_rcp_f32_e32 v49, v49
	v_rcp_f32_e32 v50, v50
	v_rcp_f32_e32 v51, v51
	s_cbranch_scc1 .LBB0_573
; DI void prompt_tile(const LAS unsigned char* kc, const LAS unsigned char* vc, const bf16x8 (&qf)[4], f32x16 (&accO)[2], float& carry, float bias2, int key0, int Q0, int r, int h2) {
;     ...
;         if (need_mask) {
;             asm volatile("" ::: "memory");
;             const int lim = Q0 + r - key0 - 4 * h2;
; #pragma unroll
;             for (int kb = 0; kb < 2; ++kb)
; #pragma unroll
;                 for (int pq = 0; pq < 8; ++pq) { const int ko = 32 * kb + ((2 * pq) & 3) + 8 * ((2 * pq) >> 2); if (ko >= lim) kp[kb][pq].x = 1.f; if (ko + 1 >= lim) kp[kb][pq].y = 1.f; }
;         }
	v_add_u32_e32 v3, s74, v191
	v_or_b32_e32 v39, s12, v206
	v_sub_u32_e32 v3, v3, v39
	v_cmp_lt_i32_e32 vcc, 0, v3
	v_cmp_lt_i32_e64 s[20:21], 1, v3
	s_or_b64 vcc, s[20:21], vcc
	v_cndmask_b32_e32 v56, 1.0, v56, vcc
	v_cndmask_b32_e64 v57, 1.0, v57, s[20:21]
	v_cmp_lt_i32_e32 vcc, 2, v3
	v_cmp_lt_i32_e64 s[20:21], 3, v3
	s_or_b64 vcc, s[20:21], vcc
	v_cndmask_b32_e32 v4, 1.0, v4, vcc
	v_cndmask_b32_e64 v5, 1.0, v5, s[20:21]
	v_cmp_lt_i32_e32 vcc, 8, v3
	v_cmp_lt_i32_e64 s[20:21], 9, v3
	s_or_b64 vcc, s[20:21], vcc
	v_cndmask_b32_e32 v216, 1.0, v216, vcc
	v_cndmask_b32_e64 v217, 1.0, v217, s[20:21]
	v_cmp_lt_i32_e32 vcc, 10, v3
	v_cmp_lt_i32_e64 s[20:21], 11, v3
	s_or_b64 vcc, s[20:21], vcc
	v_cndmask_b32_e32 v62, 1.0, v62, vcc
	v_cndmask_b32_e64 v63, 1.0, v63, s[20:21]
	v_cmp_lt_i32_e32 vcc, 16, v3
	v_cmp_lt_i32_e64 s[20:21], 17, v3
	s_or_b64 vcc, s[20:21], vcc
	v_cndmask_b32_e32 v58, 1.0, v58, vcc
	v_cndmask_b32_e64 v59, 1.0, v59, s[20:21]
	v_cmp_lt_i32_e32 vcc, 18, v3
	v_cmp_lt_i32_e64 s[20:21], 19, v3
	s_or_b64 vcc, s[20:21], vcc
	v_cndmask_b32_e32 v60, 1.0, v60, vcc
	v_cndmask_b32_e64 v61, 1.0, v61, s[20:21]
	v_cmp_lt_i32_e32 vcc, 24, v3
	v_cmp_lt_i32_e64 s[20:21], 25, v3
	s_or_b64 vcc, s[20:21], vcc
	v_cndmask_b32_e32 v64, 1.0, v64, vcc
	v_cndmask_b32_e64 v65, 1.0, v65, s[20:21]
	v_cmp_lt_i32_e32 vcc, 26, v3
	v_cmp_lt_i32_e64 s[20:21], 27, v3
	s_or_b64 vcc, s[20:21], vcc
	v_cndmask_b32_e32 v66, 1.0, v66, vcc
	v_cndmask_b32_e64 v67, 1.0, v67, s[20:21]
	v_cmp_lt_i32_e32 vcc, 32, v3
	v_cmp_lt_i32_e64 s[20:21], 33, v3
	s_or_b64 vcc, s[20:21], vcc
	v_cndmask_b32_e32 v40, 1.0, v40, vcc
	v_cndmask_b32_e64 v41, 1.0, v41, s[20:21]
	v_cmp_lt_i32_e32 vcc, 34, v3
	v_cmp_lt_i32_e64 s[20:21], 35, v3
	s_or_b64 vcc, s[20:21], vcc
	v_cndmask_b32_e32 v42, 1.0, v42, vcc
	v_cndmask_b32_e64 v43, 1.0, v43, s[20:21]
	v_cmp_lt_i32_e32 vcc, 40, v3
	v_cmp_lt_i32_e64 s[20:21], 41, v3
	s_or_b64 vcc, s[20:21], vcc
	v_cndmask_b32_e32 v68, 1.0, v68, vcc
	v_cndmask_b32_e64 v69, 1.0, v69, s[20:21]
	v_cmp_lt_i32_e32 vcc, 42, v3
	v_cmp_lt_i32_e64 s[20:21], 43, v3
	s_or_b64 vcc, s[20:21], vcc
	v_cndmask_b32_e32 v70, 1.0, v70, vcc
	v_cndmask_b32_e64 v71, 1.0, v71, s[20:21]
	v_cmp_lt_i32_e32 vcc, 48, v3
	v_cmp_lt_i32_e64 s[20:21], 49, v3
	s_or_b64 vcc, s[20:21], vcc
	v_cndmask_b32_e32 v44, 1.0, v44, vcc
	v_cndmask_b32_e64 v45, 1.0, v45, s[20:21]
	v_cmp_lt_i32_e32 vcc, 50, v3
	v_cmp_lt_i32_e64 s[20:21], 51, v3
	s_or_b64 vcc, s[20:21], vcc
	v_cndmask_b32_e32 v46, 1.0, v46, vcc
	v_cndmask_b32_e64 v47, 1.0, v47, s[20:21]
	v_cmp_lt_i32_e32 vcc, 56, v3
	v_cmp_lt_i32_e64 s[20:21], 57, v3
	s_or_b64 vcc, s[20:21], vcc
	v_cndmask_b32_e32 v48, 1.0, v48, vcc
	v_cndmask_b32_e64 v49, 1.0, v49, s[20:21]
	v_cmp_lt_i32_e32 vcc, 58, v3
	v_cmp_lt_i32_e64 s[20:21], 59, v3
	s_or_b64 vcc, s[20:21], vcc
	v_cndmask_b32_e32 v50, 1.0, v50, vcc
	v_cndmask_b32_e64 v51, 1.0, v51, s[20:21]

; #define LAS __attribute__((address_space(3)))
; DI float fexp2(float x) { return __builtin_amdgcn_exp2f(x); }
; DI float frcp(float x) { return __builtin_amdgcn_rcpf(x); }
; #define MFMA32(a, b, c) __builtin_amdgcn_mfma_f32_32x32x16_bf16((a), (b), (c), 0, 0, 0)
; DI void prompt_tile(const LAS unsigned char* kc, const LAS unsigned char* vc, const bf16x8 (&qf)[4], f32x16 (&accO)[2], float& carry, float bias2, int key0, int Q0, int r, int h2) {
;     ...
;     if (key0 < Q0 + 31) {
;         f32x16 sk[2];
; #pragma unroll
;         for (int kb = 0; kb < 2; ++kb) {
; #pragma unroll
;             for (int i = 0; i < 16; ++i) sk[kb][i] = bias2;
; #pragma unroll
;             for (int s = 0; s < 4; ++s) { const bf16x8 a = *(const LAS bf16x8*)(kc + (32 * kb + r) * (KLD * 2) + (16 * s + 8 * h2) * 2); sk[kb] = MFMA32(a, qf[s], sk[kb]); }
;         }
;         const bool need_mask = key0 + 63 >= Q0;
;         f32x2 kp[2][8];
; #pragma unroll
;         for (int kb = 0; kb < 2; ++kb)
; #pragma unroll
;             for (int pq = 0; pq < 8; ++pq) {
;                 f32x2 e2; e2.x = fexp2(sk[kb][2 * pq]); e2.y = fexp2(sk[kb][2 * pq + 1]);
;                 const f32x2 d2 = e2 + 1.0f;
;                 f32x2 k2; k2.x = frcp(d2.x); k2.y = frcp(d2.y);
;                 kp[kb][pq] = k2;
;             }
.LBB0_633:
	s_max_i32 s16, s75, 2
	s_lshl_b32 s16, s16, 6
	s_addk_i32 s16, 0xff80
	s_ashr_i32 s17, s16, 31
	s_lshl_b64 s[18:19], s[16:17], 10
	v_lshl_add_u64 v[4:5], v[208:209], 0, s[18:19]
	global_load_dwordx4 v[168:171], v[4:5], off
	v_lshl_add_u64 v[4:5], s[16:17], 1, v[210:211]
	global_load_dwordx4 v[172:175], v[4:5], off
	v_cndmask_b32_e64 v3, 0, 1, s[12:13]
	v_cmp_ne_u32_e64 s[18:19], 1, v3
	s_andn2_b64 vcc, exec, s[12:13]
	s_cbranch_vccnz .LBB0_646
	s_lshl_b32 s12, s75, 6
	s_add_i32 s13, s74, 31
	v_readlane_b32 s16, v243, 24
	s_cmp_ge_i32 s12, s13
	v_readlane_b32 s17, v243, 25
	s_cbranch_scc1 .LBB0_638
	s_mul_i32 s13, s2, 0x2400
	v_add3_u32 v3, v218, s13, v219
	ds_read_b128 v[224:227], v3
	ds_read_b128 v[228:231], v3 offset:32
	ds_read_b128 v[248:251], v3 offset:64
	ds_read_b128 v[252:255], v3 offset:96
	v_mov_b32_e32 v39, v38
	v_mov_b64_e32 v[40:41], v[38:39]
	v_mov_b64_e32 v[42:43], v[38:39]
	v_mov_b64_e32 v[44:45], v[38:39]
	v_mov_b64_e32 v[46:47], v[38:39]
	v_mov_b64_e32 v[48:49], v[38:39]
	v_mov_b64_e32 v[50:51], v[38:39]
	v_mov_b64_e32 v[52:53], v[38:39]
	v_mov_b64_e32 v[54:55], v[38:39]
	s_or_b32 s13, s12, 63
	s_cmp_lt_i32 s13, s74
	s_waitcnt lgkmcnt(3)
	v_mfma_f32_32x32x16_bf16 v[56:71], v[224:227], v[72:75], v[40:55]
	ds_read_b128 v[224:227], v3 offset:4608
	s_waitcnt lgkmcnt(3)
	v_mfma_f32_32x32x16_bf16 v[56:71], v[228:231], v[84:87], v[56:71]
	ds_read_b128 v[228:231], v3 offset:4640
	s_waitcnt lgkmcnt(3)
	v_mfma_f32_32x32x16_bf16 v[56:71], v[248:251], v[80:83], v[56:71]
	ds_read_b128 v[248:251], v3 offset:4672
	s_waitcnt lgkmcnt(3)
	v_mfma_f32_32x32x16_bf16 v[56:71], v[252:255], v[76:79], v[56:71]
	ds_read_b128 v[252:255], v3 offset:4704
	s_waitcnt lgkmcnt(3)
	v_mfma_f32_32x32x16_bf16 v[40:55], v[224:227], v[72:75], v[40:55]
	s_nop 8
	v_exp_f32_e32 v4, v56
	v_exp_f32_e32 v5, v57
	s_nop 0
	v_pk_add_f32 v[4:5], v[4:5], 1.0 op_sel_hi:[1,0]
	s_waitcnt lgkmcnt(2)
	v_mfma_f32_32x32x16_bf16 v[40:55], v[228:231], v[84:87], v[40:55]
	v_rcp_f32_e32 v56, v4
	v_rcp_f32_e32 v57, v5
	v_exp_f32_e32 v4, v58
	v_exp_f32_e32 v5, v59
	v_exp_f32_e32 v58, v60
	v_exp_f32_e32 v59, v61
	s_waitcnt lgkmcnt(1)
	v_mfma_f32_32x32x16_bf16 v[40:55], v[248:251], v[80:83], v[40:55]
	v_add_f32_e64 v58, v58, 1.0
	v_add_f32_e64 v59, v59, 1.0
	v_exp_f32_e32 v60, v66
	v_rcp_f32_e32 v216, v58
	v_rcp_f32_e32 v217, v59
	v_exp_f32_e32 v58, v62
	v_exp_f32_e32 v59, v63
	s_waitcnt lgkmcnt(0)
	v_mfma_f32_32x32x16_bf16 v[40:55], v[252:255], v[76:79], v[40:55]
	v_add_f32_e64 v58, v58, 1.0
	v_add_f32_e64 v59, v59, 1.0
	v_exp_f32_e32 v61, v67
	v_rcp_f32_e32 v62, v58
	v_rcp_f32_e32 v63, v59
	v_exp_f32_e32 v58, v64
	v_exp_f32_e32 v59, v65
	v_exp_f32_e32 v64, v68
	s_nop 3
	v_exp_f32_e32 v44, v44
	v_exp_f32_e32 v45, v45
	v_exp_f32_e32 v65, v69
	v_exp_f32_e32 v66, v70
	v_exp_f32_e32 v67, v71
	v_pk_add_f32 v[44:45], v[44:45], 1.0 op_sel_hi:[1,0]
	v_exp_f32_e32 v40, v40
	v_rcp_f32_e32 v68, v44
	v_rcp_f32_e32 v69, v45
	v_exp_f32_e32 v44, v46
	v_exp_f32_e32 v45, v47
	v_exp_f32_e32 v41, v41
	v_exp_f32_e32 v42, v42
	v_exp_f32_e32 v43, v43
	v_pk_add_f32 v[44:45], v[44:45], 1.0 op_sel_hi:[1,0]
	v_exp_f32_e32 v46, v50
	v_rcp_f32_e32 v70, v44
	v_rcp_f32_e32 v71, v45
	v_exp_f32_e32 v44, v48
	v_exp_f32_e32 v45, v49
	v_exp_f32_e32 v47, v51
	v_exp_f32_e32 v48, v52
	v_exp_f32_e32 v49, v53
	v_exp_f32_e32 v50, v54
	v_exp_f32_e32 v51, v55
	v_pk_add_f32 v[4:5], v[4:5], 1.0 op_sel_hi:[1,0]
	v_pk_add_f32 v[58:59], v[58:59], 1.0 op_sel_hi:[1,0]
	v_pk_add_f32 v[60:61], v[60:61], 1.0 op_sel_hi:[1,0]
	v_pk_add_f32 v[64:65], v[64:65], 1.0 op_sel_hi:[1,0]
	v_pk_add_f32 v[66:67], v[66:67], 1.0 op_sel_hi:[1,0]
	v_pk_add_f32 v[40:41], v[40:41], 1.0 op_sel_hi:[1,0]
	v_pk_add_f32 v[42:43], v[42:43], 1.0 op_sel_hi:[1,0]
	v_pk_add_f32 v[44:45], v[44:45], 1.0 op_sel_hi:[1,0]
	v_pk_add_f32 v[46:47], v[46:47], 1.0 op_sel_hi:[1,0]
	v_pk_add_f32 v[48:49], v[48:49], 1.0 op_sel_hi:[1,0]
	v_pk_add_f32 v[50:51], v[50:51], 1.0 op_sel_hi:[1,0]
	v_rcp_f32_e32 v4, v4
	v_rcp_f32_e32 v5, v5
	v_rcp_f32_e32 v58, v58
	v_rcp_f32_e32 v59, v59
	v_rcp_f32_e32 v60, v60
	v_rcp_f32_e32 v61, v61
	v_rcp_f32_e32 v64, v64
	v_rcp_f32_e32 v65, v65
	v_rcp_f32_e32 v66, v66
	v_rcp_f32_e32 v67, v67
	v_rcp_f32_e32 v40, v40
	v_rcp_f32_e32 v41, v41
	v_rcp_f32_e32 v42, v42
	v_rcp_f32_e32 v43, v43
	v_rcp_f32_e32 v44, v44
	v_rcp_f32_e32 v45, v45
	v_rcp_f32_e32 v46, v46
	v_rcp_f32_e32 v47, v47
	v_rcp_f32_e32 v48, v48
	v_rcp_f32_e32 v49, v49
	v_rcp_f32_e32 v50, v50
	v_rcp_f32_e32 v51, v51
	s_cbranch_scc1 .LBB0_637
; DI void prompt_tile(const LAS unsigned char* kc, const LAS unsigned char* vc, const bf16x8 (&qf)[4], f32x16 (&accO)[2], float& carry, float bias2, int key0, int Q0, int r, int h2) {
;     ...
;         if (need_mask) {
;             asm volatile("" ::: "memory");
;             const int lim = Q0 + r - key0 - 4 * h2;
; #pragma unroll
;             for (int kb = 0; kb < 2; ++kb)
; #pragma unroll
;                 for (int pq = 0; pq < 8; ++pq) { const int ko = 32 * kb + ((2 * pq) & 3) + 8 * ((2 * pq) >> 2); if (ko >= lim) kp[kb][pq].x = 1.f; if (ko + 1 >= lim) kp[kb][pq].y = 1.f; }
;         }
	v_add_u32_e32 v3, s74, v191
	v_or_b32_e32 v39, s12, v206
	v_sub_u32_e32 v3, v3, v39
	v_cmp_lt_i32_e32 vcc, 0, v3
	v_cmp_lt_i32_e64 s[20:21], 1, v3
	s_or_b64 vcc, s[20:21], vcc
	v_cndmask_b32_e32 v56, 1.0, v56, vcc
	v_cndmask_b32_e64 v57, 1.0, v57, s[20:21]
	v_cmp_lt_i32_e32 vcc, 2, v3
	v_cmp_lt_i32_e64 s[20:21], 3, v3
	s_or_b64 vcc, s[20:21], vcc
	v_cndmask_b32_e32 v4, 1.0, v4, vcc
	v_cndmask_b32_e64 v5, 1.0, v5, s[20:21]
	v_cmp_lt_i32_e32 vcc, 8, v3
	v_cmp_lt_i32_e64 s[20:21], 9, v3
	s_or_b64 vcc, s[20:21], vcc
	v_cndmask_b32_e32 v216, 1.0, v216, vcc
	v_cndmask_b32_e64 v217, 1.0, v217, s[20:21]
	v_cmp_lt_i32_e32 vcc, 10, v3
	v_cmp_lt_i32_e64 s[20:21], 11, v3
	s_or_b64 vcc, s[20:21], vcc
	v_cndmask_b32_e32 v62, 1.0, v62, vcc
	v_cndmask_b32_e64 v63, 1.0, v63, s[20:21]
	v_cmp_lt_i32_e32 vcc, 16, v3
	v_cmp_lt_i32_e64 s[20:21], 17, v3
	s_or_b64 vcc, s[20:21], vcc
	v_cndmask_b32_e32 v58, 1.0, v58, vcc
	v_cndmask_b32_e64 v59, 1.0, v59, s[20:21]
	v_cmp_lt_i32_e32 vcc, 18, v3
	v_cmp_lt_i32_e64 s[20:21], 19, v3
	s_or_b64 vcc, s[20:21], vcc
	v_cndmask_b32_e32 v60, 1.0, v60, vcc
	v_cndmask_b32_e64 v61, 1.0, v61, s[20:21]
	v_cmp_lt_i32_e32 vcc, 24, v3
	v_cmp_lt_i32_e64 s[20:21], 25, v3
	s_or_b64 vcc, s[20:21], vcc
	v_cndmask_b32_e32 v64, 1.0, v64, vcc
	v_cndmask_b32_e64 v65, 1.0, v65, s[20:21]
	v_cmp_lt_i32_e32 vcc, 26, v3
	v_cmp_lt_i32_e64 s[20:21], 27, v3
	s_or_b64 vcc, s[20:21], vcc
	v_cndmask_b32_e32 v66, 1.0, v66, vcc
	v_cndmask_b32_e64 v67, 1.0, v67, s[20:21]
	v_cmp_lt_i32_e32 vcc, 32, v3
	v_cmp_lt_i32_e64 s[20:21], 33, v3
	s_or_b64 vcc, s[20:21], vcc
	v_cndmask_b32_e32 v40, 1.0, v40, vcc
	v_cndmask_b32_e64 v41, 1.0, v41, s[20:21]
	v_cmp_lt_i32_e32 vcc, 34, v3
	v_cmp_lt_i32_e64 s[20:21], 35, v3
	s_or_b64 vcc, s[20:21], vcc
	v_cndmask_b32_e32 v42, 1.0, v42, vcc
	v_cndmask_b32_e64 v43, 1.0, v43, s[20:21]
	v_cmp_lt_i32_e32 vcc, 40, v3
	v_cmp_lt_i32_e64 s[20:21], 41, v3
	s_or_b64 vcc, s[20:21], vcc
	v_cndmask_b32_e32 v68, 1.0, v68, vcc
	v_cndmask_b32_e64 v69, 1.0, v69, s[20:21]
	v_cmp_lt_i32_e32 vcc, 42, v3
	v_cmp_lt_i32_e64 s[20:21], 43, v3
	s_or_b64 vcc, s[20:21], vcc
	v_cndmask_b32_e32 v70, 1.0, v70, vcc
	v_cndmask_b32_e64 v71, 1.0, v71, s[20:21]
	v_cmp_lt_i32_e32 vcc, 48, v3
	v_cmp_lt_i32_e64 s[20:21], 49, v3
	s_or_b64 vcc, s[20:21], vcc
	v_cndmask_b32_e32 v44, 1.0, v44, vcc
	v_cndmask_b32_e64 v45, 1.0, v45, s[20:21]
	v_cmp_lt_i32_e32 vcc, 50, v3
	v_cmp_lt_i32_e64 s[20:21], 51, v3
	s_or_b64 vcc, s[20:21], vcc
	v_cndmask_b32_e32 v46, 1.0, v46, vcc
	v_cndmask_b32_e64 v47, 1.0, v47, s[20:21]
	v_cmp_lt_i32_e32 vcc, 56, v3
	v_cmp_lt_i32_e64 s[20:21], 57, v3
	s_or_b64 vcc, s[20:21], vcc
	v_cndmask_b32_e32 v48, 1.0, v48, vcc
	v_cndmask_b32_e64 v49, 1.0, v49, s[20:21]
	v_cmp_lt_i32_e32 vcc, 58, v3
	v_cmp_lt_i32_e64 s[20:21], 59, v3
	s_or_b64 vcc, s[20:21], vcc
	v_cndmask_b32_e32 v50, 1.0, v50, vcc
	v_cndmask_b32_e64 v51, 1.0, v51, s[20:21]

; __global__ void __launch_bounds__(NTHR, 2) mega(Params p) {
	.amdhsa_kernel _Z4mega6Params
		.amdhsa_group_segment_fixed_size 0
		.amdhsa_private_segment_fixed_size 0
		.amdhsa_kernarg_size 560
		.amdhsa_user_sgpr_count 2
		.amdhsa_user_sgpr_dispatch_ptr 0
		.amdhsa_user_sgpr_queue_ptr 0
		.amdhsa_user_sgpr_kernarg_segment_ptr 1
		.amdhsa_user_sgpr_dispatch_id 0
		.amdhsa_user_sgpr_kernarg_preload_length 0
		.amdhsa_user_sgpr_kernarg_preload_offset 0
		.amdhsa_user_sgpr_private_segment_size 0
		.amdhsa_uses_dynamic_stack 0
		.amdhsa_enable_private_segment 0
		.amdhsa_system_sgpr_workgroup_id_x 1
		.amdhsa_system_sgpr_workgroup_id_y 0
		.amdhsa_system_sgpr_workgroup_id_z 0
		.amdhsa_system_sgpr_workgroup_info 0
		.amdhsa_system_vgpr_workitem_id 0
		.amdhsa_next_free_vgpr 256
		.amdhsa_next_free_sgpr 102
		.amdhsa_accum_offset 256
		.amdhsa_reserve_vcc 1
		.amdhsa_float_round_mode_32 0
		.amdhsa_float_round_mode_16_64 0
		.amdhsa_float_denorm_mode_32 3
		.amdhsa_float_denorm_mode_16_64 3
		.amdhsa_dx10_clamp 1
		.amdhsa_ieee_mode 1
		.amdhsa_fp16_overflow 0
		.amdhsa_tg_split 0
		.amdhsa_exception_fp_ieee_invalid_op 0
		.amdhsa_exception_fp_denorm_src 0
		.amdhsa_exception_fp_ieee_div_zero 0
		.amdhsa_exception_fp_ieee_overflow 0
		.amdhsa_exception_fp_ieee_underflow 0
		.amdhsa_exception_fp_ieee_inexact 0
		.amdhsa_exception_int_div_zero 0
	.end_amdhsa_kernel

; __global__ void __launch_bounds__(NTHR, 2) mega(Params p) {
amdhsa.kernels:
  - .agpr_count:     0
    .args:
      - .offset:         0
        .size:           304
        .value_kind:     by_value
      - .offset:         304
        .size:           4
        .value_kind:     hidden_block_count_x
      - .offset:         308
        .size:           4
        .value_kind:     hidden_block_count_y
      - .offset:         312
        .size:           4
        .value_kind:     hidden_block_count_z
      - .offset:         316
        .size:           2
        .value_kind:     hidden_group_size_x
      - .offset:         318
        .size:           2
        .value_kind:     hidden_group_size_y
      - .offset:         320
        .size:           2
        .value_kind:     hidden_group_size_z
      - .offset:         322
        .size:           2
        .value_kind:     hidden_remainder_x
      - .offset:         324
        .size:           2
        .value_kind:     hidden_remainder_y
      - .offset:         326
        .size:           2
        .value_kind:     hidden_remainder_z
      - .offset:         344
        .size:           8
        .value_kind:     hidden_global_offset_x
      - .offset:         352
        .size:           8
        .value_kind:     hidden_global_offset_y
      - .offset:         360
        .size:           8
        .value_kind:     hidden_global_offset_z
      - .offset:         368
        .size:           2
        .value_kind:     hidden_grid_dims
      - .offset:         424
        .size:           4
        .value_kind:     hidden_dynamic_lds_size
    .group_segment_fixed_size: 0
    .kernarg_segment_align: 8
    .kernarg_segment_size: 560
    .language:       OpenCL C
    .language_version:
      - 2
      - 0
    .max_flat_workgroup_size: 512
    .name:           _Z4mega6Params
    .private_segment_fixed_size: 0
    .sgpr_count:     108
    .sgpr_spill_count: 168
    .symbol:         _Z4mega6Params.kd
    .uniform_work_group_size: 1
    .uses_dynamic_stack: false
    .vgpr_count:     256
    .vgpr_spill_count: 0
    .wavefront_size: 64
